# P11c LN2: lane column mapping k*256+4l (was 16l): every row load/store instruction covers contiguous full cache lines
# speedup vs baseline: 1.0183x; 1.0183x over previous
; DI void phase11c(const Params& P) {
;     ...
;   float4 gg[4], bb[4];
; #pragma unroll
;   for (int k = 0; k < 4; ++k) { gg[k] = *reinterpret_cast<const float4*>(P.ln2g + lane * 16 + k * 4); bb[k] = *reinterpret_cast<const float4*>(P.ln2b + lane * 16 + k * 4); }
;   const int t0 = VB * 4 + wid, tstep = NVB * 4;
;   h8 nx0, nx1, na0, na1;
;   {
;     const int tt = t0 < NTOK ? t0 : 0;
;     nx0 = *reinterpret_cast<const h8*>(h1h + (long)tt * 1024 + lane * 16); nx1 = *reinterpret_cast<const h8*>(h1h + (long)tt * 1024 + lane * 16 + 8);
;     na0 = *reinterpret_cast<const h8*>(Zp + (long)tt * 1024 + lane * 16); na1 = *reinterpret_cast<const h8*>(Zp + (long)tt * 1024 + lane * 16 + 8);
;   }
;   for (int t = t0; t < NTOK; t += tstep) {
;     const h8 x0 = nx0, x1 = nx1, a0 = na0, a1 = na1;
;     {
;       const int tn = t + tstep < NTOK ? t + tstep : t;
;       nx0 = *reinterpret_cast<const h8*>(h1h + (long)tn * 1024 + lane * 16); nx1 = *reinterpret_cast<const h8*>(h1h + (long)tn * 1024 + lane * 16 + 8);
;       na0 = *reinterpret_cast<const h8*>(Zp + (long)tn * 1024 + lane * 16); na1 = *reinterpret_cast<const h8*>(Zp + (long)tn * 1024 + lane * 16 + 8);
;     }
;     float z[16]; float s = 0.f;
; #pragma unroll
;     for (int k = 0; k < 8; ++k) { z[k] = (float)a0[k] + ALPHA * (float)x0[k]; z[8 + k] = (float)a1[k] + ALPHA * (float)x1[k]; }
.LBB0_1634:
	s_or_b64 exec, exec, s[0:1]
	v_readlane_b32 s2, v254, 39
	v_readlane_b32 s3, v254, 40
	s_waitcnt lgkmcnt(0)
	s_barrier
	s_and_saveexec_b64 s[0:1], s[2:3]
	s_cbranch_execz .LBB0_1637
	v_and_b32_e32 v32, 0x3f0, v209
	v_readlane_b32 s0, v254, 0
	v_mov_b32_e32 v33, v32
	v_readlane_b32 s4, v254, 4
	v_readlane_b32 s5, v254, 5
	v_readlane_b32 s6, v254, 6
	v_readlane_b32 s7, v254, 7
	s_nop 2
	global_load_dwordx4 v[0:3], v33, s[4:5] offset:3072
	s_nop 0
	global_load_dwordx4 v[4:7], v33, s[6:7] offset:3072
	global_load_dwordx4 v[8:11], v33, s[4:5] offset:2048
	global_load_dwordx4 v[12:15], v33, s[6:7] offset:2048
	global_load_dwordx4 v[16:19], v33, s[4:5] offset:1024
	global_load_dwordx4 v[20:23], v33, s[6:7] offset:1024
	global_load_dwordx4 v[24:27], v33, s[4:5]
	global_load_dwordx4 v[28:31], v33, s[6:7]
	v_readlane_b32 s1, v254, 1
	s_add_u32 s0, s78, 0xa000000
	s_addc_u32 s1, s79, 0
	v_lshrrev_b32_e32 v50, 1, v32
	v_lshlrev_b64 v[32:33], 11, v[210:211]
	v_mov_b32_e32 v51, 0
	v_lshl_add_u64 v[34:35], s[0:1], 0, v[32:33]
	v_lshl_add_u64 v[32:33], s[54:55], 0, v[32:33]
	v_lshl_add_u64 v[34:35], v[34:35], 0, v[50:51]
	v_lshl_add_u64 v[48:49], v[32:33], 0, v[50:51]
	global_load_dwordx2 v[36:37], v[34:35], off offset:1024
	global_load_dwordx2 v[38:39], v[34:35], off offset:1536
	global_load_dwordx2 v[44:45], v[34:35], off
	global_load_dwordx2 v[46:47], v[34:35], off offset:512
	s_nop 0
	global_load_dwordx2 v[32:33], v[48:49], off offset:1024
	global_load_dwordx2 v[34:35], v[48:49], off offset:1536
	global_load_dwordx2 v[40:41], v[48:49], off
	global_load_dwordx2 v[42:43], v[48:49], off offset:512
	v_readlane_b32 s2, v254, 2
	v_readlane_b32 s3, v254, 3
	s_lshl_b32 s2, s64, 3
	v_lshlrev_b64 v[52:53], 12, v[210:211]
	v_lshl_or_b32 v52, v208, 4, v52
	s_ashr_i32 s3, s2, 31
	v_lshl_add_u64 v[48:49], s[54:55], 0, v[50:51]
	v_lshl_add_u64 v[50:51], s[0:1], 0, v[50:51]
	v_lshl_add_u64 v[52:53], s[76:77], 0, v[52:53]
	s_lshl_b64 s[4:5], s[2:3], 12
	s_mov_b64 s[6:7], 0
	s_movk_i32 s3, 0x7fff
	s_mov_b32 s9, 0x8000
	s_mov_b32 s8, 0x3f9837f0
	v_mov_b32_e32 v54, 0x3727c5ac
	s_mov_b32 s10, 0x800000
	s_waitcnt vmcnt(0)
.LBB0_1636:
	v_add_u32_e32 v55, s2, v210
	v_cmp_gt_i32_e64 s[0:1], s9, v55
	s_waitcnt vmcnt(4)
	v_cvt_f32_f16_sdwa v57, v44 dst_sel:DWORD dst_unused:UNUSED_PAD src0_sel:WORD_1
	v_cvt_f32_f16_e32 v56, v44
	v_cvt_f32_f16_sdwa v59, v40 dst_sel:DWORD dst_unused:UNUSED_PAD src0_sel:WORD_1
	v_cvt_f32_f16_e32 v58, v40
	v_cvt_f32_f16_sdwa v61, v45 dst_sel:DWORD dst_unused:UNUSED_PAD src0_sel:WORD_1
	v_cvt_f32_f16_e32 v60, v45
	v_cvt_f32_f16_sdwa v45, v41 dst_sel:DWORD dst_unused:UNUSED_PAD src0_sel:WORD_1
	v_cvt_f32_f16_e32 v44, v41
	v_cvt_f32_f16_sdwa v41, v46 dst_sel:DWORD dst_unused:UNUSED_PAD src0_sel:WORD_1
	v_cvt_f32_f16_e32 v40, v46
	v_cvt_f32_f16_sdwa v63, v42 dst_sel:DWORD dst_unused:UNUSED_PAD src0_sel:WORD_1
	v_cvt_f32_f16_e32 v62, v42
	v_cvt_f32_f16_sdwa v65, v47 dst_sel:DWORD dst_unused:UNUSED_PAD src0_sel:WORD_1
	v_cvt_f32_f16_e32 v64, v47
	v_cvt_f32_f16_sdwa v47, v43 dst_sel:DWORD dst_unused:UNUSED_PAD src0_sel:WORD_1
	v_cvt_f32_f16_e32 v46, v43
	v_cvt_f32_f16_sdwa v43, v36 dst_sel:DWORD dst_unused:UNUSED_PAD src0_sel:WORD_1
	v_cvt_f32_f16_e32 v42, v36
	v_cvt_f32_f16_sdwa v67, v32 dst_sel:DWORD dst_unused:UNUSED_PAD src0_sel:WORD_1
	v_cvt_f32_f16_e32 v66, v32
	v_cvt_f32_f16_sdwa v69, v37 dst_sel:DWORD dst_unused:UNUSED_PAD src0_sel:WORD_1
	v_cvt_f32_f16_e32 v68, v37
	v_cvt_f32_f16_sdwa v37, v33 dst_sel:DWORD dst_unused:UNUSED_PAD src0_sel:WORD_1
	v_cvt_f32_f16_e32 v36, v33
	v_cvt_f32_f16_sdwa v33, v38 dst_sel:DWORD dst_unused:UNUSED_PAD src0_sel:WORD_1
	v_cvt_f32_f16_e32 v32, v38
	v_cvt_f32_f16_sdwa v71, v34 dst_sel:DWORD dst_unused:UNUSED_PAD src0_sel:WORD_1
	v_cvt_f32_f16_e32 v70, v34
	v_cvt_f32_f16_sdwa v73, v39 dst_sel:DWORD dst_unused:UNUSED_PAD src0_sel:WORD_1
	v_cvt_f32_f16_e32 v72, v39
	v_cvt_f32_f16_sdwa v39, v35 dst_sel:DWORD dst_unused:UNUSED_PAD src0_sel:WORD_1
	v_cvt_f32_f16_e32 v38, v35
	v_cndmask_b32_e64 v34, v210, v55, s[0:1]
	v_ashrrev_i32_e32 v35, 31, v34
	v_lshlrev_b64 v[34:35], 11, v[34:35]
	v_lshl_add_u64 v[74:75], v[48:49], 0, v[34:35]
	v_lshl_add_u64 v[76:77], v[50:51], 0, v[34:35]
	v_pk_fma_f32 v[56:57], v[58:59], s[8:9], v[56:57] op_sel_hi:[1,0,1]
	v_pk_fma_f32 v[58:59], v[44:45], s[8:9], v[60:61] op_sel_hi:[1,0,1]
	v_pk_fma_f32 v[60:61], v[62:63], s[8:9], v[40:41] op_sel_hi:[1,0,1]
	v_pk_fma_f32 v[62:63], v[46:47], s[8:9], v[64:65] op_sel_hi:[1,0,1]
	v_pk_fma_f32 v[64:65], v[66:67], s[8:9], v[42:43] op_sel_hi:[1,0,1]
	v_pk_fma_f32 v[66:67], v[36:37], s[8:9], v[68:69] op_sel_hi:[1,0,1]
	v_pk_fma_f32 v[68:69], v[70:71], s[8:9], v[32:33] op_sel_hi:[1,0,1]
	v_pk_fma_f32 v[70:71], v[38:39], s[8:9], v[72:73] op_sel_hi:[1,0,1]
	global_load_dwordx2 v[40:41], v[74:75], off
	global_load_dwordx2 v[42:43], v[74:75], off offset:512
	global_load_dwordx2 v[32:33], v[74:75], off offset:1024
	global_load_dwordx2 v[34:35], v[74:75], off offset:1536
; DI float wave_sum(float v) { v = dpp_row_sum_f0(v); return (rl_f(v, 0) + rl_f(v, 16)) + (rl_f(v, 32) + rl_f(v, 48)); }
; DI void phase11c(const Params& P) {
;     ...
;       nx0 = *reinterpret_cast<const h8*>(h1h + (long)tn * 1024 + lane * 16); nx1 = *reinterpret_cast<const h8*>(h1h + (long)tn * 1024 + lane * 16 + 8);
;       na0 = *reinterpret_cast<const h8*>(Zp + (long)tn * 1024 + lane * 16); na1 = *reinterpret_cast<const h8*>(Zp + (long)tn * 1024 + lane * 16 + 8);
;     }
;     float z[16]; float s = 0.f;
; #pragma unroll
;     for (int k = 0; k < 8; ++k) { z[k] = (float)a0[k] + ALPHA * (float)x0[k]; z[8 + k] = (float)a1[k] + ALPHA * (float)x1[k]; }
; #pragma unroll
;     for (int k = 0; k < 16; ++k) s += z[k];
;     const float mu = wave_sum(s) * (1.f / 1024.f);
;     float q = 0.f;
; #pragma unroll
;     for (int k = 0; k < 16; ++k) { const float d = z[k] - mu; q += d * d; }
;     const float rstd = rsqrtf(wave_sum(q) * (1.f / 1024.f) + 1e-5f);
; #pragma unroll
;     for (int k = 0; k < 4; ++k) {
;       float4 o;
;       o.x = (z[4 * k] - mu) * rstd * gg[k].x + bb[k].x; o.y = (z[4 * k + 1] - mu) * rstd * gg[k].y + bb[k].y;
;       o.z = (z[4 * k + 2] - mu) * rstd * gg[k].z + bb[k].z; o.w = (z[4 * k + 3] - mu) * rstd * gg[k].w + bb[k].w;
;       *reinterpret_cast<float4*>(P.out + (long)t * 1024 + lane * 16 + k * 4) = o;
	global_load_dwordx2 v[44:45], v[76:77], off
	global_load_dwordx2 v[46:47], v[76:77], off offset:512
	global_load_dwordx2 v[36:37], v[76:77], off offset:1024
	global_load_dwordx2 v[38:39], v[76:77], off offset:1536
	v_cmp_lt_i32_e32 vcc, s3, v55
	v_mov_b32_e32 v210, v55
	v_add_f32_e32 v55, 0, v56
	v_add_f32_e32 v55, v57, v55
	v_add_f32_e32 v55, v58, v55
	v_add_f32_e32 v55, v59, v55
	v_add_f32_e32 v55, v60, v55
	v_add_f32_e32 v55, v61, v55
	v_add_f32_e32 v55, v62, v55
	v_add_f32_e32 v55, v63, v55
	v_add_f32_e32 v55, v64, v55
	v_add_f32_e32 v55, v65, v55
	v_add_f32_e32 v55, v66, v55
	v_add_f32_e32 v55, v67, v55
	v_add_f32_e32 v55, v68, v55
	v_add_f32_e32 v55, v69, v55
	v_add_f32_e32 v55, v70, v55
	v_add_f32_e32 v55, v71, v55
	s_or_b64 s[6:7], vcc, s[6:7]
	s_nop 0
	v_add_f32_dpp v55, v55, v55 quad_perm:[1,0,3,2] row_mask:0xf bank_mask:0xf bound_ctrl:1
	s_nop 1
	v_add_f32_dpp v55, v55, v55 quad_perm:[2,3,0,1] row_mask:0xf bank_mask:0xf bound_ctrl:1
	s_nop 1
	v_add_f32_dpp v55, v55, v55 row_half_mirror row_mask:0xf bank_mask:0xf bound_ctrl:1
	s_nop 1
	v_add_f32_dpp v55, v55, v55 row_mirror row_mask:0xf bank_mask:0xf bound_ctrl:1
	s_nop 0
	v_readlane_b32 s11, v55, 16
	v_readlane_b32 s12, v55, 48
	v_readlane_b32 s0, v55, 0
	v_readlane_b32 s1, v55, 32
	v_mov_b32_e32 v72, s11
	v_mov_b32_e32 v73, s12
	v_pk_add_f32 v[72:73], s[0:1], v[72:73]
	s_nop 0
	v_add_f32_e32 v55, v72, v73
	v_mul_f32_e32 v72, 0x3a800000, v55
	v_pk_add_f32 v[56:57], v[56:57], v[72:73] op_sel_hi:[1,0] neg_lo:[0,1] neg_hi:[0,1]
	v_pk_add_f32 v[58:59], v[58:59], v[72:73] op_sel_hi:[1,0] neg_lo:[0,1] neg_hi:[0,1]
	v_pk_add_f32 v[60:61], v[60:61], v[72:73] op_sel_hi:[1,0] neg_lo:[0,1] neg_hi:[0,1]
	v_pk_add_f32 v[62:63], v[62:63], v[72:73] op_sel_hi:[1,0] neg_lo:[0,1] neg_hi:[0,1]
	v_pk_add_f32 v[64:65], v[64:65], v[72:73] op_sel_hi:[1,0] neg_lo:[0,1] neg_hi:[0,1]
	v_pk_add_f32 v[66:67], v[66:67], v[72:73] op_sel_hi:[1,0] neg_lo:[0,1] neg_hi:[0,1]
	v_pk_add_f32 v[68:69], v[68:69], v[72:73] op_sel_hi:[1,0] neg_lo:[0,1] neg_hi:[0,1]
	v_pk_add_f32 v[70:71], v[70:71], v[72:73] op_sel_hi:[1,0] neg_lo:[0,1] neg_hi:[0,1]
	v_pk_mul_f32 v[72:73], v[56:57], v[56:57]
	v_pk_mul_f32 v[74:75], v[58:59], v[58:59]
	v_add_f32_e32 v55, v72, v73
	v_add_f32_e32 v55, v74, v55
	v_pk_mul_f32 v[76:77], v[60:61], v[60:61]
	v_add_f32_e32 v55, v75, v55
	v_add_f32_e32 v55, v76, v55
	v_pk_mul_f32 v[78:79], v[62:63], v[62:63]
	v_add_f32_e32 v55, v77, v55
	v_add_f32_e32 v55, v78, v55
	v_pk_mul_f32 v[80:81], v[64:65], v[64:65]
	v_add_f32_e32 v55, v79, v55
	v_add_f32_e32 v55, v80, v55
	v_pk_mul_f32 v[82:83], v[66:67], v[66:67]
	v_add_f32_e32 v55, v81, v55
	v_add_f32_e32 v55, v82, v55
	v_pk_mul_f32 v[84:85], v[68:69], v[68:69]
	v_add_f32_e32 v55, v83, v55
	v_add_f32_e32 v55, v84, v55
	v_pk_mul_f32 v[86:87], v[70:71], v[70:71]
	v_add_f32_e32 v55, v85, v55
	v_add_f32_e32 v55, v86, v55
	v_add_f32_e32 v55, v87, v55
	s_nop 1
	v_add_f32_dpp v55, v55, v55 quad_perm:[1,0,3,2] row_mask:0xf bank_mask:0xf bound_ctrl:1
	s_nop 1
	v_add_f32_dpp v55, v55, v55 quad_perm:[2,3,0,1] row_mask:0xf bank_mask:0xf bound_ctrl:1
	s_nop 1
	v_add_f32_dpp v55, v55, v55 row_half_mirror row_mask:0xf bank_mask:0xf bound_ctrl:1
	s_nop 1
	v_add_f32_dpp v55, v55, v55 row_mirror row_mask:0xf bank_mask:0xf bound_ctrl:1
	s_nop 0
	v_readlane_b32 s11, v55, 16
	v_readlane_b32 s12, v55, 48
	v_readlane_b32 s0, v55, 0
	v_readlane_b32 s1, v55, 32
	v_mov_b32_e32 v72, s11
	v_mov_b32_e32 v73, s12
	v_pk_add_f32 v[72:73], s[0:1], v[72:73]
	s_nop 0
	v_add_f32_e32 v55, v72, v73
	v_fmamk_f32 v55, v55, 0x3a800000, v54
	v_mul_f32_e32 v72, 0x4b800000, v55
	v_cmp_gt_f32_e32 vcc, s10, v55
	s_nop 1
	v_cndmask_b32_e32 v55, v55, v72, vcc
	v_rsq_f32_e32 v55, v55
	s_nop 0
	v_mul_f32_e32 v72, 0x45800000, v55
	v_cndmask_b32_e32 v72, v55, v72, vcc
	v_pk_mul_f32 v[56:57], v[56:57], v[72:73] op_sel_hi:[1,0]
	v_pk_mul_f32 v[58:59], v[58:59], v[72:73] op_sel_hi:[1,0]
	v_pk_mul_f32 v[60:61], v[60:61], v[72:73] op_sel_hi:[1,0]
	v_pk_mul_f32 v[62:63], v[62:63], v[72:73] op_sel_hi:[1,0]
	v_pk_mul_f32 v[64:65], v[64:65], v[72:73] op_sel_hi:[1,0]
	v_pk_mul_f32 v[66:67], v[66:67], v[72:73] op_sel_hi:[1,0]
	v_pk_mul_f32 v[68:69], v[68:69], v[72:73] op_sel_hi:[1,0]
	v_pk_mul_f32 v[70:71], v[70:71], v[72:73] op_sel_hi:[1,0]
	v_pk_fma_f32 v[56:57], v[24:25], v[56:57], v[28:29]
	v_pk_fma_f32 v[58:59], v[26:27], v[58:59], v[30:31]
	v_pk_fma_f32 v[60:61], v[16:17], v[60:61], v[20:21]
	v_pk_fma_f32 v[62:63], v[18:19], v[62:63], v[22:23]
	v_pk_fma_f32 v[64:65], v[8:9], v[64:65], v[12:13]
	v_pk_fma_f32 v[66:67], v[10:11], v[66:67], v[14:15]
	v_pk_fma_f32 v[68:69], v[0:1], v[68:69], v[4:5]
	v_pk_fma_f32 v[70:71], v[2:3], v[70:71], v[6:7]
	global_store_dwordx4 v[52:53], v[56:59], off
	global_store_dwordx4 v[52:53], v[60:63], off offset:1024
	global_store_dwordx4 v[52:53], v[64:67], off offset:2048
	global_store_dwordx4 v[52:53], v[68:71], off offset:3072
	v_lshl_add_u64 v[52:53], v[52:53], 0, s[4:5]
	s_andn2_b64 exec, exec, s[6:7]
	s_cbranch_execnz .LBB0_1636
